# attnepi with the two counted waits that mix older loads and newer stores reverted to full drains (HGRN chunk header, G2/G4 residual loads): robustness against store acks overtaking older loads
# baseline (speedup 1.0000x reference)
; __device__ __forceinline__ void hgrn_phase(const Params& p, int e, char* lds) {
;     ...
;       *(u32x4*)(RQ + lr * PK + lc8 * 2) = gq; *(u32x4*)(RZ + lr * PK + lc8 * 2) = gz;
;       *(u32x4*)(RV + vr * PV + vc8 * 2) = gv0; *(u32x4*)(RV + (vr + 32) * PV + vc8 * 2) = gv1;
;       LBAR();
;       float qf[8], kk[8], cl[8]; float run = 0.f;
; #pragma unroll
;       for (int i = 0; i < 8; ++i) { const int t = 8 * rq + i; const float z = bf2f(*(const unsigned short*)(RZ + t * PK + k * 2)); qf[i] = bf2f(*(const unsigned short*)(RQ + t * PK + k * 2));
;         const float sg = __builtin_amdgcn_rcpf(1.0f + __builtin_amdgcn_exp2f(-L2E * z)); const float f = lbk + (1.0f - lbk) * sg;
;         run += __builtin_amdgcn_logf(f); cl[i] = run; kk[i] = 1.0f - f; }
;       TOT[rq * 64 + k] = run;
;       unsigned short rvv[16];
; #pragma unroll
;       for (int i = 0; i < 16; ++i) rvv[i] = *(const unsigned short*)(RV + (16 * jg + i) * PV + vv * 2);
;       u32x4 vpa, vpb;
;       vpa.x = rvv[0] | ((unsigned)rvv[1] << 16); vpa.y = rvv[2] | ((unsigned)rvv[3] << 16); vpa.z = rvv[4] | ((unsigned)rvv[5] << 16); vpa.w = rvv[6] | ((unsigned)rvv[7] << 16);
;       vpb.x = rvv[8] | ((unsigned)rvv[9] << 16); vpb.y = rvv[10] | ((unsigned)rvv[11] << 16); vpb.z = rvv[12] | ((unsigned)rvv[13] << 16); vpb.w = rvv[14] | ((unsigned)rvv[15] << 16);
;       LBAR();
;       { float tt[8];
; #pragma unroll
;         for (int r8 = 0; r8 < 8; ++r8) tt[r8] = TOT[r8 * 64 + k];
;         const float mid = (tt[0] + tt[1]) + (tt[2] + tt[3]), last = mid + ((tt[4] + tt[5]) + (tt[6] + tt[7]));
;         float off = 0.f;
; #pragma unroll
;         for (int r8 = 0; r8 < 7; ++r8) off += (r8 < rq) ? tt[r8] : 0.f;
;         const float el = __builtin_amdgcn_exp2f(last), em = __builtin_amdgcn_exp2f(fminf(-mid, 120.f)), emi = __builtin_amdgcn_exp2f(mid);
;         if (rq == 0) DD[k] = el;
;         unsigned ksw[4];
; #pragma unroll
;         for (int i = 0; i < 8; ++i) { const float cc = off + cl[i];
;           const float e1 = __builtin_amdgcn_exp2f(cc), inv1 = __builtin_amdgcn_exp2f(fminf(-cc, 120.f));
;           const float ea = fminf(e1 * em, 3.6e16f), eb = fminf(inv1 * emi, 3.6e16f), es = fminf(inv1 * el, 1.0f);
;           const int t = 8 * rq + i;
;           const unsigned w0 = cvtpk(qf[i] * e1, qf[i] * ea), w1 = cvtpk(kk[i] * eb, kk[i] * es);
.LBB0_222:
	s_waitcnt vmcnt(0)
	ds_write_b128 v143, v[16:19]
	ds_write_b128 v143, v[20:23] offset:9216
	ds_write_b128 v152, v[24:27] offset:18432
	ds_write_b128 v152, v[28:31] offset:27136
	s_waitcnt lgkmcnt(0)
	s_barrier
	ds_read_u16 v16, v100 offset:9216
	ds_read_u16 v17, v100 offset:9360
	ds_read_u16 v18, v100 offset:9504
	ds_read_u16 v19, v100 offset:9648
	ds_read_u16 v20, v100 offset:9792
	ds_read_u16 v21, v100 offset:9936
	ds_read_u16 v22, v100 offset:10080
	ds_read_u16 v23, v100 offset:10224
	s_waitcnt lgkmcnt(6)
	v_lshlrev_b32_e32 v17, 16, v17
	v_mul_f32_e32 v17, 0xbfb8aa3b, v17
	v_exp_f32_e32 v17, v17
	v_lshlrev_b32_e32 v16, 16, v16
	v_mul_f32_e32 v16, 0xbfb8aa3b, v16
	s_waitcnt lgkmcnt(5)
	v_lshlrev_b32_e32 v18, 16, v18
	v_exp_f32_e32 v16, v16
	v_add_f32_e32 v17, 1.0, v17
	v_mul_f32_e32 v18, 0xbfb8aa3b, v18
	v_rcp_f32_e32 v17, v17
	v_exp_f32_e32 v18, v18
	v_add_f32_e32 v16, 1.0, v16
	v_rcp_f32_e32 v16, v16
	v_fma_f32 v33, v163, v17, v162
	v_add_f32_e32 v17, 1.0, v18
	s_waitcnt lgkmcnt(4)
	v_lshlrev_b32_e32 v18, 16, v19
	v_mul_f32_e32 v18, 0xbfb8aa3b, v18
	v_rcp_f32_e32 v17, v17
	v_exp_f32_e32 v18, v18
	v_fma_f32 v32, v163, v16, v162
	v_log_f32_e32 v16, v32
	v_log_f32_e32 v19, v33
	v_fma_f32 v34, v163, v17, v162
	v_add_f32_e32 v18, 1.0, v18
	v_log_f32_e32 v17, v34
	v_rcp_f32_e32 v18, v18
	v_add_f32_e32 v31, 0, v16
	v_add_f32_e32 v30, v31, v19
	v_add_f32_e32 v29, v30, v17
	v_fma_f32 v37, v163, v18, v162
	s_waitcnt lgkmcnt(3)
	v_lshlrev_b32_e32 v17, 16, v20
	s_waitcnt lgkmcnt(2)
	v_lshlrev_b32_e32 v18, 16, v21
	v_mul_f32_e32 v17, 0xbfb8aa3b, v17
	v_mul_f32_e32 v18, 0xbfb8aa3b, v18
	v_log_f32_e32 v16, v37
	v_exp_f32_e32 v17, v17
	v_exp_f32_e32 v18, v18
	ds_read_u16 v57, v100
	ds_read_u16 v55, v100 offset:144
	ds_read_u16 v54, v100 offset:288
	ds_read_u16 v52, v100 offset:432
	ds_read_u16 v50, v100 offset:576
	ds_read_u16 v49, v100 offset:720
	ds_read_u16 v47, v100 offset:864
	ds_read_u16 v45, v100 offset:1008
	v_add_f32_e32 v27, v29, v16
	v_add_f32_e32 v16, 1.0, v17
	v_add_f32_e32 v17, 1.0, v18
	s_waitcnt lgkmcnt(9)
	v_lshlrev_b32_e32 v18, 16, v22
	v_mul_f32_e32 v18, 0xbfb8aa3b, v18
	v_rcp_f32_e32 v17, v17
	v_exp_f32_e32 v18, v18
	v_rcp_f32_e32 v16, v16
	v_fma_f32 v39, v163, v17, v162
	v_add_f32_e32 v17, 1.0, v18
	s_waitcnt lgkmcnt(8)
	v_lshlrev_b32_e32 v18, 16, v23
	v_mul_f32_e32 v18, 0xbfb8aa3b, v18
	v_exp_f32_e32 v18, v18
	v_rcp_f32_e32 v17, v17
	v_fma_f32 v38, v163, v16, v162
	v_log_f32_e32 v16, v38
	v_add_f32_e32 v18, 1.0, v18
	v_rcp_f32_e32 v18, v18
	v_log_f32_e32 v19, v39
	v_fma_f32 v40, v163, v17, v162
	v_log_f32_e32 v17, v40
	v_fma_f32 v41, v163, v18, v162
	v_add_f32_e32 v28, v27, v16
	v_log_f32_e32 v16, v41
	v_add_f32_e32 v26, v28, v19
	v_add_f32_e32 v25, v26, v17
	v_add_f32_e32 v24, v25, v16
	ds_write_b32 v107, v24
	ds_read_u16 v35, v153 offset:18432
	ds_read_u16 v36, v153 offset:18704
	ds_read_u16 v43, v153 offset:18976
	ds_read_u16 v44, v153 offset:19248
	ds_read_u16 v46, v153 offset:19520
	ds_read_u16 v48, v153 offset:19792
	ds_read_u16 v51, v153 offset:20064
	ds_read_u16 v53, v153 offset:20336
	ds_read_u16 v56, v153 offset:20608
	ds_read_u16 v58, v153 offset:20880
	ds_read_u16 v59, v153 offset:21152
	ds_read_u16 v60, v153 offset:21424
	ds_read_u16 v61, v153 offset:21696
	ds_read_u16 v62, v153 offset:21968
	ds_read_u16 v63, v153 offset:22240
	ds_read_u16 v64, v153 offset:22512
	s_waitcnt lgkmcnt(0)
	s_barrier
	ds_read2st64_b32 v[20:21], v108 offset0:2 offset1:3
	ds_read2st64_b32 v[18:19], v108 offset0:4 offset1:5
	ds_read2st64_b32 v[16:17], v108 offset0:6 offset1:7
	ds_read2st64_b32 v[22:23], v108 offset1:1
	s_waitcnt lgkmcnt(3)
	v_add_f32_e32 v42, v20, v21
	s_waitcnt lgkmcnt(2)
	v_add_f32_e32 v65, v18, v19
	s_waitcnt lgkmcnt(1)
	v_add_f32_e32 v17, v16, v17
	v_add_f32_e32 v17, v65, v17
	s_waitcnt lgkmcnt(0)
	v_add_f32_e32 v65, v22, v23
	v_add_f32_e32 v42, v65, v42
	v_add_f32_e32 v17, v42, v17
	v_exp_f32_e32 v17, v17
	s_and_saveexec_b64 s[26:27], s[42:43]
	ds_write_b32 v109, v17
	s_or_b64 exec, exec, s[26:27]
	v_add_f32_e32 v22, 0, v22
	v_cndmask_b32_e64 v22, 0, v22, s[64:65]
	v_cndmask_b32_e64 v23, 0, v23, s[66:67]
	v_add_f32_e32 v22, v22, v23
	v_cndmask_b32_e64 v20, 0, v20, s[68:69]
	v_add_f32_e32 v20, v22, v20
	v_cndmask_b32_e64 v21, 0, v21, s[70:71]
	v_add_f32_e32 v20, v20, v21
	v_cndmask_b32_e64 v18, 0, v18, s[72:73]
	v_add_f32_e32 v18, v20, v18
	v_cndmask_b32_e64 v19, 0, v19, s[74:75]
	v_add_f32_e32 v18, v18, v19
	v_cndmask_b32_e64 v16, 0, v16, s[76:77]
	v_add_f32_e32 v16, v18, v16
	v_max_f32_e64 v18, -v42, -v42
	v_min_f32_e32 v18, 0x42f00000, v18
	v_exp_f32_e32 v21, v18
	v_add_f32_e32 v18, v31, v16
	v_exp_f32_e32 v19, v18
	v_min_f32_e64 v18, -v18, s33
	v_exp_f32_e32 v22, v42
	v_exp_f32_e32 v18, v18
	v_lshlrev_b32_e32 v57, 16, v57
	v_mul_f32_e32 v20, v21, v19
	v_sub_f32_e32 v32, 1.0, v32
	v_mul_f32_e32 v23, v22, v18
	v_mul_f32_e32 v18, v17, v18
	v_min_f32_e32 v20, 0x5affcb9e, v20
	v_min_f32_e32 v18, 1.0, v18
	v_mul_f32_e32 v19, v19, v57
	v_min_f32_e32 v23, 0x5affcb9e, v23
	v_mul_f32_e32 v20, v20, v57
	v_cvt_pk_bf16_f32 v19, v19, v20
	v_mul_f32_e32 v18, v32, v18
	v_mul_f32_e32 v20, v32, v23
	v_cvt_pk_bf16_f32 v18, v20, v18
	ds_write_b16 v181, v19
	ds_write_b16_d16_hi v181, v19 offset:9216
	ds_write_b16 v181, v18 offset:18432
	v_add_f32_e32 v19, v30, v16
	v_exp_f32_e32 v20, v19
	v_min_f32_e64 v19, -v19, s33
	v_exp_f32_e32 v19, v19
	v_lshlrev_b32_e32 v55, 16, v55
	v_mul_f32_e32 v23, v21, v20
	v_sub_f32_e32 v33, 1.0, v33
	v_mul_f32_e32 v30, v22, v19
	v_mul_f32_e32 v19, v17, v19
	v_min_f32_e32 v23, 0x5affcb9e, v23
	v_min_f32_e32 v19, 1.0, v19
	v_mul_f32_e32 v20, v20, v55
	v_min_f32_e32 v30, 0x5affcb9e, v30
; #define GAS __attribute__((address_space(1)))
; __device__ __forceinline__ void hgrn_phase(const Params& p, int e, char* lds) {
;     ...
;         for (int i = 0; i < 8; ++i) { const float cc = off + cl[i];
;           const float e1 = __builtin_amdgcn_exp2f(cc), inv1 = __builtin_amdgcn_exp2f(fminf(-cc, 120.f));
;           const float ea = fminf(e1 * em, 3.6e16f), eb = fminf(inv1 * emi, 3.6e16f), es = fminf(inv1 * el, 1.0f);
;           const int t = 8 * rq + i;
;           const unsigned w0 = cvtpk(qf[i] * e1, qf[i] * ea), w1 = cvtpk(kk[i] * eb, kk[i] * es);
;           *(unsigned short*)(QD + t * PK + k * 2) = (unsigned short)(w0 & 0xffffu);
;           *(unsigned short*)(QA + t * PK + k * 2) = (unsigned short)(w0 >> 16);
;           *(unsigned short*)(KB + t * PK + k * 2) = (unsigned short)(w1 & 0xffffu);
;           if (i & 1) ksw[i >> 1] |= (w1 & 0xffff0000u); else ksw[i >> 1] = (w1 >> 16); }
;         *(u32x4*)(KS + k * PJ + rq * 16) = (u32x4){ksw[0], ksw[1], ksw[2], ksw[3]};
;         *(u32x4*)(VT + vv * PJ + jg * 32) = vpa; *(u32x4*)(VT + vv * PJ + jg * 32 + 16) = vpb; }
;       LBAR();
;       if (c + 1 < SEQ / 64) { const int bc = base0 + rsb * 64 * (c + 1); const int o0 = bc + rsb * lr;
;         gq = *(const GAS u32x4*)(bigc + (size_t)(unsigned)(o0 + qcol)); gz = *(const GAS u32x4*)(bigc + (size_t)(unsigned)(o0 + zcol));
;         gv0 = *(const GAS u32x4*)(bigc + (size_t)(unsigned)(bc + rsb * vr + vcol)); gv1 = *(const GAS u32x4*)(bigc + (size_t)(unsigned)(bc + rsb * (vr + 32) + vcol)); }
;     ...
;       f32x4 oacc[4];
;       const int wq = wave >> 1, vt0 = 4 * (wave & 1);
;       { const int ttA = 2 * (wave & 1); const char* STp = ST + pb * (128 * PK);
;         bf16x8 fa[2], fb0[2], fb1[2], fqd[2], fs[4][2];
; #pragma unroll
;         for (int ks = 0; ks < 2; ++ks) { fa[ks] = ldfrag(KB, 16 * wq + fr, PK, ks * 32 + fq_ * 8); fb0[ks] = ldfrag(QA, 16 * ttA + fr, PK, ks * 32 + fq_ * 8); fb1[ks] = ldfrag(QA, 16 * (ttA + 1) + fr, PK, ks * 32 + fq_ * 8);
;           fqd[ks] = ldfrag(QD, 16 * wq + fr, PK, ks * 32 + fq_ * 8);
; #pragma unroll
;           for (int n = 0; n < 4; ++n) fs[n][ks] = ldfrag(STp, 16 * (vt0 + n) + fr, PK, ks * 32 + fq_ * 8); }
;         HWAIT();
;         f32x4 acc0 = (f32x4){0.f, 0.f, 0.f, 0.f}, acc1 = acc0;
; #pragma unroll
;         for (int n = 0; n < 4; ++n) oacc[n] = acc0;
; #pragma unroll
;         for (int ks = 0; ks < 2; ++ks) {
	v_mul_f32_e32 v23, v23, v55
	v_cvt_pk_bf16_f32 v20, v20, v23
	v_mul_f32_e32 v19, v33, v19
	v_mul_f32_e32 v23, v33, v30
	v_cvt_pk_bf16_f32 v19, v23, v19
	ds_write_b16 v181, v20 offset:144
	ds_write_b16_d16_hi v181, v20 offset:9360
	ds_write_b16 v181, v19 offset:18576
	v_add_f32_e32 v20, v29, v16
	v_exp_f32_e32 v23, v20
	v_min_f32_e64 v20, -v20, s33
	v_exp_f32_e32 v20, v20
	v_lshrrev_b32_e32 v18, 16, v18
	v_and_or_b32 v18, v19, s13, v18
	v_mul_f32_e32 v19, v21, v23
	v_lshlrev_b32_e32 v54, 16, v54
	v_min_f32_e32 v19, 0x5affcb9e, v19
	v_mul_f32_e32 v29, v22, v20
	v_mul_f32_e32 v20, v17, v20
	v_sub_f32_e32 v34, 1.0, v34
	v_min_f32_e32 v20, 1.0, v20
	v_mul_f32_e32 v19, v19, v54
	v_min_f32_e32 v29, 0x5affcb9e, v29
	v_mul_f32_e32 v23, v23, v54
	v_cvt_pk_bf16_f32 v19, v23, v19
	v_mul_f32_e32 v20, v34, v20
	v_mul_f32_e32 v23, v34, v29
	v_cvt_pk_bf16_f32 v20, v23, v20
	ds_write_b16 v181, v19 offset:288
	ds_write_b16_d16_hi v181, v19 offset:9504
	ds_write_b16 v181, v20 offset:18720
	v_add_f32_e32 v19, v27, v16
	v_exp_f32_e32 v23, v19
	v_min_f32_e64 v19, -v19, s33
	v_exp_f32_e32 v19, v19
	v_lshlrev_b32_e32 v52, 16, v52
	v_mul_f32_e32 v27, v21, v23
	v_sub_f32_e32 v37, 1.0, v37
	v_mul_f32_e32 v29, v22, v19
	v_mul_f32_e32 v19, v17, v19
	v_min_f32_e32 v27, 0x5affcb9e, v27
	v_min_f32_e32 v19, 1.0, v19
	v_mul_f32_e32 v23, v23, v52
	v_min_f32_e32 v29, 0x5affcb9e, v29
	v_mul_f32_e32 v27, v27, v52
	v_cvt_pk_bf16_f32 v23, v23, v27
	v_mul_f32_e32 v19, v37, v19
	v_mul_f32_e32 v27, v37, v29
	v_cvt_pk_bf16_f32 v19, v27, v19
	ds_write_b16 v181, v23 offset:432
	ds_write_b16_d16_hi v181, v23 offset:9648
	ds_write_b16 v181, v19 offset:18864
	v_add_f32_e32 v23, v28, v16
	v_exp_f32_e32 v27, v23
	v_min_f32_e64 v23, -v23, s33
	v_exp_f32_e32 v23, v23
	v_lshrrev_b32_e32 v20, 16, v20
	v_and_or_b32 v19, v19, s13, v20
	v_mul_f32_e32 v20, v21, v27
	v_lshlrev_b32_e32 v50, 16, v50
	v_min_f32_e32 v20, 0x5affcb9e, v20
	v_mul_f32_e32 v28, v22, v23
	v_mul_f32_e32 v23, v17, v23
	v_sub_f32_e32 v65, 1.0, v38
	v_min_f32_e32 v23, 1.0, v23
	v_mul_f32_e32 v20, v20, v50
	v_min_f32_e32 v28, 0x5affcb9e, v28
	v_mul_f32_e32 v27, v27, v50
	v_cvt_pk_bf16_f32 v20, v27, v20
	v_mul_f32_e32 v23, v65, v23
	v_mul_f32_e32 v27, v65, v28
	v_cvt_pk_bf16_f32 v23, v27, v23
	ds_write_b16 v182, v20 offset:576
	ds_write_b16_d16_hi v182, v20 offset:9792
	ds_write_b16 v182, v23 offset:19008
	v_add_f32_e32 v20, v26, v16
	v_exp_f32_e32 v26, v20
	v_min_f32_e64 v20, -v20, s33
	v_exp_f32_e32 v20, v20
	v_lshlrev_b32_e32 v49, 16, v49
	v_mul_f32_e32 v27, v21, v26
	v_sub_f32_e32 v66, 1.0, v39
	v_mul_f32_e32 v28, v22, v20
	v_mul_f32_e32 v20, v17, v20
	v_min_f32_e32 v27, 0x5affcb9e, v27
	v_min_f32_e32 v20, 1.0, v20
	v_mul_f32_e32 v26, v26, v49
	v_min_f32_e32 v28, 0x5affcb9e, v28
	v_mul_f32_e32 v27, v27, v49
	v_cvt_pk_bf16_f32 v26, v26, v27
	v_mul_f32_e32 v20, v66, v20
	v_add_f32_e32 v25, v25, v16
	v_mul_f32_e32 v27, v66, v28
	v_cvt_pk_bf16_f32 v20, v27, v20
	ds_write_b16 v182, v26 offset:720
	ds_write_b16_d16_hi v182, v26 offset:9936
	ds_write_b16 v182, v20 offset:19152
	v_exp_f32_e32 v26, v25
	v_min_f32_e64 v25, -v25, s33
	v_exp_f32_e32 v25, v25
	v_lshrrev_b32_e32 v23, 16, v23
	v_and_or_b32 v20, v20, s13, v23
	v_mul_f32_e32 v23, v21, v26
	v_lshlrev_b32_e32 v67, 16, v47
	v_min_f32_e32 v23, 0x5affcb9e, v23
	v_mul_f32_e32 v27, v22, v25
	v_mul_f32_e32 v25, v17, v25
	v_sub_f32_e32 v68, 1.0, v40
	v_min_f32_e32 v25, 1.0, v25
	v_mul_f32_e32 v23, v23, v67
	v_min_f32_e32 v27, 0x5affcb9e, v27
	v_mul_f32_e32 v26, v26, v67
	v_cvt_pk_bf16_f32 v23, v26, v23
	v_mul_f32_e32 v25, v68, v25
	v_add_f32_e32 v16, v24, v16
	v_mul_f32_e32 v26, v68, v27
	v_cvt_pk_bf16_f32 v25, v26, v25
	ds_write_b16 v182, v23 offset:864
	ds_write_b16_d16_hi v182, v23 offset:10080
	ds_write_b16 v182, v25 offset:19296
	v_exp_f32_e32 v23, v16
	v_min_f32_e64 v16, -v16, s33
	v_exp_f32_e32 v16, v16
	v_lshlrev_b32_e32 v69, 16, v45
	v_mul_f32_e32 v21, v21, v23
	v_min_f32_e32 v21, 0x5affcb9e, v21
	v_mul_f32_e32 v22, v22, v16
	v_mul_f32_e32 v16, v17, v16
	v_sub_f32_e32 v70, 1.0, v41
	v_min_f32_e32 v22, 0x5affcb9e, v22
	v_min_f32_e32 v16, 1.0, v16
	v_mul_f32_e32 v17, v23, v69
	v_mul_f32_e32 v21, v21, v69
	v_lshrrev_b32_e32 v24, 16, v25
	v_cvt_pk_bf16_f32 v17, v17, v21
	v_mul_f32_e32 v21, v70, v22
	v_mul_f32_e32 v16, v70, v16
	v_cvt_pk_bf16_f32 v16, v21, v16
	v_perm_b32 v41, v64, v63, s7
	v_and_or_b32 v21, v16, s13, v24
	v_perm_b32 v40, v62, v61, s7
	v_perm_b32 v39, v60, v59, s7
	v_perm_b32 v38, v58, v56, s7
	v_perm_b32 v47, v53, v51, s7
	v_perm_b32 v46, v48, v46, s7
	v_perm_b32 v45, v44, v43, s7
	v_perm_b32 v44, v36, v35, s7
	ds_write_b16 v182, v17 offset:1008
	ds_write_b16_d16_hi v182, v17 offset:10224
	ds_write_b16 v182, v16 offset:19440
	ds_write_b128 v154, v[18:21] offset:27648
	ds_write_b128 v155, v[44:47] offset:36864
	ds_write_b128 v183, v[38:41] offset:36880
	s_waitcnt lgkmcnt(0)
	s_barrier
	v_add_u32_e32 v16, s8, v172
	v_add_u32_e32 v20, v171, v170
	v_add_u32_e32 v24, vcc_hi, v169
	v_add_u32_e32 v28, vcc_hi, v168
	global_load_dwordx4 v[16:19], v16, s[30:31]
	s_nop 0
	global_load_dwordx4 v[20:23], v20, s[30:31]
	s_nop 0
	global_load_dwordx4 v[24:27], v24, s[30:31]
	s_nop 0
	global_load_dwordx4 v[28:31], v28, s[30:31]
	s_and_b32 s14, vcc_lo, 1
	s_mul_i32 s5, s14, 0x4800
	v_add_u32_e32 v32, s5, v122
	v_add_u32_e32 v36, v32, v101
	v_add_u32_e32 v37, v32, v119
	v_add_u32_e32 v38, v32, v120
	v_add_u32_e32 v39, v32, v121
	v_add_u32_e32 v173, v111, v110
	ds_read_b128 v[76:79], v156 offset:18432
	ds_read_b128 v[56:59], v156 offset:18496
	ds_read_b128 v[52:55], v173 offset:9216
	ds_read_b128 v[68:71], v173 offset:9280
	ds_read_b128 v[84:87], v173 offset:11520
	ds_read_b128 v[64:67], v173 offset:11584
	ds_read_b128 v[72:75], v156
	ds_read_b128 v[32:35], v156 offset:64
	ds_read_b128 v[80:83], v36 offset:64512
	ds_read_b128 v[48:51], v36 offset:64576
	ds_read_b128 v[88:91], v37 offset:64512
	ds_read_b128 v[44:47], v37 offset:64576
	ds_read_b128 v[92:95], v38 offset:64512
	ds_read_b128 v[40:43], v38 offset:64576
	ds_read_b128 v[96:99], v39 offset:64512
	ds_read_b128 v[36:39], v39 offset:64576
	v_mov_b32_e32 v145, v144
	v_mov_b32_e32 v146, v144
	v_mov_b32_e32 v147, v144
	v_mov_b64_e32 v[60:61], v[144:145]
	v_mov_b64_e32 v[62:63], v[146:147]
	s_and_saveexec_b64 s[26:27], s[44:45]
	s_cbranch_execz .LBB0_226
	s_waitcnt lgkmcnt(13)
	v_mfma_f32_16x16x32_bf16 v[60:63], v[76:79], v[52:55], 0

; __device__ __forceinline__ void hgrn_phase(const Params& p, int e, char* lds) {
;     ...
;       *(u32x4*)(RQ + lr * PK + lc8 * 2) = gq; *(u32x4*)(RZ + lr * PK + lc8 * 2) = gz;
;       *(u32x4*)(RV + vr * PV + vc8 * 2) = gv0; *(u32x4*)(RV + (vr + 32) * PV + vc8 * 2) = gv1;
;       LBAR();
;       float qf[8], kk[8], cl[8]; float run = 0.f;
; #pragma unroll
;       for (int i = 0; i < 8; ++i) { const int t = 8 * rq + i; const float z = bf2f(*(const unsigned short*)(RZ + t * PK + k * 2)); qf[i] = bf2f(*(const unsigned short*)(RQ + t * PK + k * 2));
;         const float sg = __builtin_amdgcn_rcpf(1.0f + __builtin_amdgcn_exp2f(-L2E * z)); const float f = lbk + (1.0f - lbk) * sg;
;         run += __builtin_amdgcn_logf(f); cl[i] = run; kk[i] = 1.0f - f; }
;       TOT[rq * 64 + k] = run;
;       unsigned short rvv[16];
; #pragma unroll
;       for (int i = 0; i < 16; ++i) rvv[i] = *(const unsigned short*)(RV + (16 * jg + i) * PV + vv * 2);
;       u32x4 vpa, vpb;
;       vpa.x = rvv[0] | ((unsigned)rvv[1] << 16); vpa.y = rvv[2] | ((unsigned)rvv[3] << 16); vpa.z = rvv[4] | ((unsigned)rvv[5] << 16); vpa.w = rvv[6] | ((unsigned)rvv[7] << 16);
;       vpb.x = rvv[8] | ((unsigned)rvv[9] << 16); vpb.y = rvv[10] | ((unsigned)rvv[11] << 16); vpb.z = rvv[12] | ((unsigned)rvv[13] << 16); vpb.w = rvv[14] | ((unsigned)rvv[15] << 16);
;       LBAR();
;       { float tt[8];
; #pragma unroll
;         for (int r8 = 0; r8 < 8; ++r8) tt[r8] = TOT[r8 * 64 + k];
;         const float mid = (tt[0] + tt[1]) + (tt[2] + tt[3]), last = mid + ((tt[4] + tt[5]) + (tt[6] + tt[7]));
;         float off = 0.f;
; #pragma unroll
;         for (int r8 = 0; r8 < 7; ++r8) off += (r8 < rq) ? tt[r8] : 0.f;
;         const float el = __builtin_amdgcn_exp2f(last), em = __builtin_amdgcn_exp2f(fminf(-mid, 120.f)), emi = __builtin_amdgcn_exp2f(mid);
;         if (rq == 0) DD[k] = el;
;         unsigned ksw[4];
; #pragma unroll
;         for (int i = 0; i < 8; ++i) { const float cc = off + cl[i];
;           const float e1 = __builtin_amdgcn_exp2f(cc), inv1 = __builtin_amdgcn_exp2f(fminf(-cc, 120.f));
;           const float ea = fminf(e1 * em, 3.6e16f), eb = fminf(inv1 * emi, 3.6e16f), es = fminf(inv1 * el, 1.0f);
;           const int t = 8 * rq + i;
;           const unsigned w0 = cvtpk(qf[i] * e1, qf[i] * ea), w1 = cvtpk(kk[i] * eb, kk[i] * es);
.LBB0_232:
	s_waitcnt vmcnt(19)
	ds_write_b128 v143, v[16:19]
	s_waitcnt vmcnt(18)
	ds_write_b128 v143, v[20:23] offset:9216
	s_waitcnt vmcnt(17)
	ds_write_b128 v152, v[24:27] offset:18432
	s_waitcnt vmcnt(0)
	ds_write_b128 v152, v[28:31] offset:27136
	s_waitcnt lgkmcnt(0)
	s_barrier
	ds_read_u16 v16, v100 offset:9216
	ds_read_u16 v17, v100 offset:9360
	ds_read_u16 v18, v100 offset:9504
	ds_read_u16 v19, v100 offset:9648
	ds_read_u16 v20, v100 offset:9792
	ds_read_u16 v21, v100 offset:9936
	ds_read_u16 v22, v100 offset:10080
	ds_read_u16 v23, v100 offset:10224
	s_waitcnt lgkmcnt(6)
	v_lshlrev_b32_e32 v17, 16, v17
	v_mul_f32_e32 v17, 0xbfb8aa3b, v17
	v_exp_f32_e32 v17, v17
	v_lshlrev_b32_e32 v16, 16, v16
	v_mul_f32_e32 v16, 0xbfb8aa3b, v16
	s_waitcnt lgkmcnt(5)
	v_lshlrev_b32_e32 v18, 16, v18
	v_exp_f32_e32 v16, v16
	v_add_f32_e32 v17, 1.0, v17
	v_mul_f32_e32 v18, 0xbfb8aa3b, v18
	v_rcp_f32_e32 v17, v17
	v_exp_f32_e32 v18, v18
	v_add_f32_e32 v16, 1.0, v16
	v_rcp_f32_e32 v16, v16
	v_fma_f32 v33, v163, v17, v162
	v_add_f32_e32 v17, 1.0, v18
	s_waitcnt lgkmcnt(4)
	v_lshlrev_b32_e32 v18, 16, v19
	v_mul_f32_e32 v18, 0xbfb8aa3b, v18
	v_rcp_f32_e32 v17, v17
	v_exp_f32_e32 v18, v18
	v_fma_f32 v32, v163, v16, v162
	v_log_f32_e32 v16, v32
	v_log_f32_e32 v19, v33
	v_fma_f32 v34, v163, v17, v162
	v_add_f32_e32 v18, 1.0, v18
	v_log_f32_e32 v17, v34
	v_rcp_f32_e32 v18, v18
	v_add_f32_e32 v31, 0, v16
	v_add_f32_e32 v30, v31, v19
	v_add_f32_e32 v29, v30, v17
	v_fma_f32 v36, v163, v18, v162
	s_waitcnt lgkmcnt(3)
	v_lshlrev_b32_e32 v17, 16, v20
	s_waitcnt lgkmcnt(2)
	v_lshlrev_b32_e32 v18, 16, v21
	v_mul_f32_e32 v17, 0xbfb8aa3b, v17
	v_mul_f32_e32 v18, 0xbfb8aa3b, v18
	v_log_f32_e32 v16, v36
	v_exp_f32_e32 v17, v17
	v_exp_f32_e32 v18, v18
	ds_read_u16 v56, v100
	ds_read_u16 v54, v100 offset:144
	ds_read_u16 v53, v100 offset:288
	ds_read_u16 v51, v100 offset:432
	ds_read_u16 v49, v100 offset:576
	ds_read_u16 v48, v100 offset:720
	ds_read_u16 v46, v100 offset:864
	ds_read_u16 v44, v100 offset:1008
	v_add_f32_e32 v27, v29, v16
	v_add_f32_e32 v16, 1.0, v17
	v_add_f32_e32 v17, 1.0, v18
	s_waitcnt lgkmcnt(9)
	v_lshlrev_b32_e32 v18, 16, v22
	v_mul_f32_e32 v18, 0xbfb8aa3b, v18
	v_rcp_f32_e32 v17, v17
	v_exp_f32_e32 v18, v18
	v_rcp_f32_e32 v16, v16
	v_fma_f32 v39, v163, v17, v162
	v_add_f32_e32 v17, 1.0, v18
	s_waitcnt lgkmcnt(8)
	v_lshlrev_b32_e32 v18, 16, v23
	v_mul_f32_e32 v18, 0xbfb8aa3b, v18
	v_exp_f32_e32 v18, v18
	v_rcp_f32_e32 v17, v17
	v_fma_f32 v38, v163, v16, v162
	v_log_f32_e32 v16, v38
	v_add_f32_e32 v18, 1.0, v18
	v_rcp_f32_e32 v18, v18
	v_log_f32_e32 v19, v39
	v_fma_f32 v40, v163, v17, v162
	v_log_f32_e32 v17, v40
	v_fmac_f32_e32 v162, v163, v18
	v_add_f32_e32 v28, v27, v16
	v_log_f32_e32 v16, v162
	v_add_f32_e32 v26, v28, v19
	v_add_f32_e32 v25, v26, v17
	v_add_f32_e32 v24, v25, v16
	ds_write_b32 v107, v24
	ds_read_u16 v35, v153 offset:18432
	ds_read_u16 v37, v153 offset:18704
	ds_read_u16 v41, v153 offset:18976
	ds_read_u16 v43, v153 offset:19248
	ds_read_u16 v45, v153 offset:19520
	ds_read_u16 v47, v153 offset:19792
	ds_read_u16 v50, v153 offset:20064
	ds_read_u16 v52, v153 offset:20336
	ds_read_u16 v55, v153 offset:20608
	ds_read_u16 v57, v153 offset:20880
	ds_read_u16 v58, v153 offset:21152
	ds_read_u16 v59, v153 offset:21424
	ds_read_u16 v60, v153 offset:21696
	ds_read_u16 v61, v153 offset:21968
	ds_read_u16 v62, v153 offset:22240
	ds_read_u16 v63, v153 offset:22512
	s_waitcnt lgkmcnt(0)
	s_barrier
	ds_read2st64_b32 v[20:21], v108 offset0:2 offset1:3
	ds_read2st64_b32 v[18:19], v108 offset0:4 offset1:5
	ds_read2st64_b32 v[16:17], v108 offset0:6 offset1:7
	ds_read2st64_b32 v[22:23], v108 offset1:1
	s_waitcnt lgkmcnt(3)
	v_add_f32_e32 v42, v20, v21
	s_waitcnt lgkmcnt(2)
	v_add_f32_e32 v64, v18, v19
	s_waitcnt lgkmcnt(1)
	v_add_f32_e32 v17, v16, v17
	v_add_f32_e32 v17, v64, v17
	s_waitcnt lgkmcnt(0)
	v_add_f32_e32 v64, v22, v23
	v_add_f32_e32 v42, v64, v42
	v_add_f32_e32 v17, v42, v17
	v_exp_f32_e32 v17, v17
	s_and_saveexec_b64 s[26:27], s[42:43]
	ds_write_b32 v109, v17
	s_or_b64 exec, exec, s[26:27]
	v_add_f32_e32 v22, 0, v22
	v_cndmask_b32_e64 v22, 0, v22, s[64:65]
	v_cndmask_b32_e64 v23, 0, v23, s[66:67]
	v_add_f32_e32 v22, v22, v23
	v_cndmask_b32_e64 v20, 0, v20, s[68:69]
	v_add_f32_e32 v20, v22, v20
	v_cndmask_b32_e64 v21, 0, v21, s[70:71]
	v_add_f32_e32 v20, v20, v21
	v_cndmask_b32_e64 v18, 0, v18, s[72:73]
	v_add_f32_e32 v18, v20, v18
	v_cndmask_b32_e64 v19, 0, v19, s[74:75]
	v_add_f32_e32 v18, v18, v19
	v_cndmask_b32_e64 v16, 0, v16, s[76:77]
	v_add_f32_e32 v16, v18, v16
	v_max_f32_e64 v18, -v42, -v42
	v_min_f32_e32 v18, 0x42f00000, v18
	v_exp_f32_e32 v21, v18
	v_add_f32_e32 v18, v31, v16
	v_exp_f32_e32 v19, v18
	v_min_f32_e64 v18, -v18, s33
	v_exp_f32_e32 v22, v42
	v_exp_f32_e32 v18, v18
	v_lshlrev_b32_e32 v56, 16, v56
	v_mul_f32_e32 v20, v21, v19
	v_sub_f32_e32 v32, 1.0, v32
	v_mul_f32_e32 v23, v22, v18
	v_mul_f32_e32 v18, v17, v18
	v_min_f32_e32 v20, 0x5affcb9e, v20
	v_min_f32_e32 v18, 1.0, v18
	v_mul_f32_e32 v19, v19, v56
	v_min_f32_e32 v23, 0x5affcb9e, v23
	v_mul_f32_e32 v20, v20, v56
	v_cvt_pk_bf16_f32 v19, v19, v20
	v_mul_f32_e32 v18, v32, v18
	v_mul_f32_e32 v20, v32, v23
	v_cvt_pk_bf16_f32 v18, v20, v18
	ds_write_b16 v181, v19
	ds_write_b16_d16_hi v181, v19 offset:9216
	ds_write_b16 v181, v18 offset:18432
	v_add_f32_e32 v19, v30, v16
	v_exp_f32_e32 v20, v19
	v_min_f32_e64 v19, -v19, s33
	v_exp_f32_e32 v19, v19
	v_lshlrev_b32_e32 v54, 16, v54
	v_mul_f32_e32 v23, v21, v20
	v_sub_f32_e32 v33, 1.0, v33
	v_mul_f32_e32 v30, v22, v19
	v_mul_f32_e32 v19, v17, v19
	v_min_f32_e32 v23, 0x5affcb9e, v23
	v_min_f32_e32 v19, 1.0, v19
; #define GAS __attribute__((address_space(1)))
; __device__ __forceinline__ void hgrn_phase(const Params& p, int e, char* lds) {
;     ...
;         for (int i = 0; i < 8; ++i) { const float cc = off + cl[i];
;           const float e1 = __builtin_amdgcn_exp2f(cc), inv1 = __builtin_amdgcn_exp2f(fminf(-cc, 120.f));
;           const float ea = fminf(e1 * em, 3.6e16f), eb = fminf(inv1 * emi, 3.6e16f), es = fminf(inv1 * el, 1.0f);
;           const int t = 8 * rq + i;
;           const unsigned w0 = cvtpk(qf[i] * e1, qf[i] * ea), w1 = cvtpk(kk[i] * eb, kk[i] * es);
;           *(unsigned short*)(QD + t * PK + k * 2) = (unsigned short)(w0 & 0xffffu);
;           *(unsigned short*)(QA + t * PK + k * 2) = (unsigned short)(w0 >> 16);
;           *(unsigned short*)(KB + t * PK + k * 2) = (unsigned short)(w1 & 0xffffu);
;           if (i & 1) ksw[i >> 1] |= (w1 & 0xffff0000u); else ksw[i >> 1] = (w1 >> 16); }
;         *(u32x4*)(KS + k * PJ + rq * 16) = (u32x4){ksw[0], ksw[1], ksw[2], ksw[3]};
;         *(u32x4*)(VT + vv * PJ + jg * 32) = vpa; *(u32x4*)(VT + vv * PJ + jg * 32 + 16) = vpb; }
;       LBAR();
;       if (c + 1 < SEQ / 64) { const int bc = base0 + rsb * 64 * (c + 1); const int o0 = bc + rsb * lr;
;         gq = *(const GAS u32x4*)(bigc + (size_t)(unsigned)(o0 + qcol)); gz = *(const GAS u32x4*)(bigc + (size_t)(unsigned)(o0 + zcol));
;         gv0 = *(const GAS u32x4*)(bigc + (size_t)(unsigned)(bc + rsb * vr + vcol)); gv1 = *(const GAS u32x4*)(bigc + (size_t)(unsigned)(bc + rsb * (vr + 32) + vcol)); }
;     ...
;       f32x4 oacc[4];
;       const int wq = wave >> 1, vt0 = 4 * (wave & 1);
;       { const int ttA = 2 * (wave & 1); const char* STp = ST + pb * (128 * PK);
;         bf16x8 fa[2], fb0[2], fb1[2], fqd[2], fs[4][2];
; #pragma unroll
;         for (int ks = 0; ks < 2; ++ks) { fa[ks] = ldfrag(KB, 16 * wq + fr, PK, ks * 32 + fq_ * 8); fb0[ks] = ldfrag(QA, 16 * ttA + fr, PK, ks * 32 + fq_ * 8); fb1[ks] = ldfrag(QA, 16 * (ttA + 1) + fr, PK, ks * 32 + fq_ * 8);
;           fqd[ks] = ldfrag(QD, 16 * wq + fr, PK, ks * 32 + fq_ * 8);
; #pragma unroll
;           for (int n = 0; n < 4; ++n) fs[n][ks] = ldfrag(STp, 16 * (vt0 + n) + fr, PK, ks * 32 + fq_ * 8); }
;         HWAIT();
;         f32x4 acc0 = (f32x4){0.f, 0.f, 0.f, 0.f}, acc1 = acc0;
; #pragma unroll
;         for (int n = 0; n < 4; ++n) oacc[n] = acc0;
; #pragma unroll
;         for (int ks = 0; ks < 2; ++ks) {
	v_mul_f32_e32 v20, v20, v54
	v_min_f32_e32 v30, 0x5affcb9e, v30
	v_mul_f32_e32 v23, v23, v54
	v_cvt_pk_bf16_f32 v20, v20, v23
	v_mul_f32_e32 v19, v33, v19
	v_mul_f32_e32 v23, v33, v30
	v_cvt_pk_bf16_f32 v19, v23, v19
	ds_write_b16 v181, v20 offset:144
	ds_write_b16_d16_hi v181, v20 offset:9360
	ds_write_b16 v181, v19 offset:18576
	v_add_f32_e32 v20, v29, v16
	v_exp_f32_e32 v23, v20
	v_min_f32_e64 v20, -v20, s33
	v_exp_f32_e32 v20, v20
	v_lshrrev_b32_e32 v18, 16, v18
	v_and_or_b32 v18, v19, s13, v18
	v_mul_f32_e32 v19, v21, v23
	v_lshlrev_b32_e32 v53, 16, v53
	v_min_f32_e32 v19, 0x5affcb9e, v19
	v_mul_f32_e32 v29, v22, v20
	v_mul_f32_e32 v20, v17, v20
	v_sub_f32_e32 v34, 1.0, v34
	v_min_f32_e32 v20, 1.0, v20
	v_mul_f32_e32 v19, v19, v53
	v_min_f32_e32 v29, 0x5affcb9e, v29
	v_mul_f32_e32 v23, v23, v53
	v_cvt_pk_bf16_f32 v19, v23, v19
	v_mul_f32_e32 v20, v34, v20
	v_mul_f32_e32 v23, v34, v29
	v_cvt_pk_bf16_f32 v20, v23, v20
	ds_write_b16 v181, v19 offset:288
	ds_write_b16_d16_hi v181, v19 offset:9504
	ds_write_b16 v181, v20 offset:18720
	v_add_f32_e32 v19, v27, v16
	v_exp_f32_e32 v23, v19
	v_min_f32_e64 v19, -v19, s33
	v_exp_f32_e32 v19, v19
	v_lshlrev_b32_e32 v51, 16, v51
	v_mul_f32_e32 v27, v21, v23
	v_sub_f32_e32 v36, 1.0, v36
	v_mul_f32_e32 v29, v22, v19
	v_mul_f32_e32 v19, v17, v19
	v_min_f32_e32 v27, 0x5affcb9e, v27
	v_min_f32_e32 v19, 1.0, v19
	v_mul_f32_e32 v23, v23, v51
	v_min_f32_e32 v29, 0x5affcb9e, v29
	v_mul_f32_e32 v27, v27, v51
	v_cvt_pk_bf16_f32 v23, v23, v27
	v_mul_f32_e32 v19, v36, v19
	v_mul_f32_e32 v27, v36, v29
	v_cvt_pk_bf16_f32 v19, v27, v19
	ds_write_b16 v181, v23 offset:432
	ds_write_b16_d16_hi v181, v23 offset:9648
	ds_write_b16 v181, v19 offset:18864
	v_add_f32_e32 v23, v28, v16
	v_exp_f32_e32 v27, v23
	v_min_f32_e64 v23, -v23, s33
	v_exp_f32_e32 v23, v23
	v_lshrrev_b32_e32 v20, 16, v20
	v_and_or_b32 v19, v19, s13, v20
	v_mul_f32_e32 v20, v21, v27
	v_lshlrev_b32_e32 v64, 16, v49
	v_min_f32_e32 v20, 0x5affcb9e, v20
	v_mul_f32_e32 v28, v22, v23
	v_mul_f32_e32 v23, v17, v23
	v_sub_f32_e32 v38, 1.0, v38
	v_min_f32_e32 v23, 1.0, v23
	v_mul_f32_e32 v20, v20, v64
	v_min_f32_e32 v28, 0x5affcb9e, v28
	v_mul_f32_e32 v27, v27, v64
	v_cvt_pk_bf16_f32 v20, v27, v20
	v_mul_f32_e32 v23, v38, v23
	v_mul_f32_e32 v27, v38, v28
	v_cvt_pk_bf16_f32 v23, v27, v23
	ds_write_b16 v182, v20 offset:576
	ds_write_b16_d16_hi v182, v20 offset:9792
	ds_write_b16 v182, v23 offset:19008
	v_add_f32_e32 v20, v26, v16
	v_exp_f32_e32 v26, v20
	v_min_f32_e64 v20, -v20, s33
	v_exp_f32_e32 v20, v20
	v_lshlrev_b32_e32 v65, 16, v48
	v_mul_f32_e32 v27, v21, v26
	v_sub_f32_e32 v39, 1.0, v39
	v_mul_f32_e32 v28, v22, v20
	v_mul_f32_e32 v20, v17, v20
	v_min_f32_e32 v27, 0x5affcb9e, v27
	v_min_f32_e32 v20, 1.0, v20
	v_mul_f32_e32 v26, v26, v65
	v_min_f32_e32 v28, 0x5affcb9e, v28
	v_mul_f32_e32 v27, v27, v65
	v_cvt_pk_bf16_f32 v26, v26, v27
	v_mul_f32_e32 v20, v39, v20
	v_add_f32_e32 v25, v25, v16
	v_mul_f32_e32 v27, v39, v28
	v_cvt_pk_bf16_f32 v20, v27, v20
	ds_write_b16 v182, v26 offset:720
	ds_write_b16_d16_hi v182, v26 offset:9936
	ds_write_b16 v182, v20 offset:19152
	v_exp_f32_e32 v26, v25
	v_min_f32_e64 v25, -v25, s33
	v_exp_f32_e32 v25, v25
	v_lshrrev_b32_e32 v23, 16, v23
	v_and_or_b32 v20, v20, s13, v23
	v_mul_f32_e32 v23, v21, v26
	v_lshlrev_b32_e32 v66, 16, v46
	v_min_f32_e32 v23, 0x5affcb9e, v23
	v_mul_f32_e32 v27, v22, v25
	v_mul_f32_e32 v25, v17, v25
	v_sub_f32_e32 v40, 1.0, v40
	v_min_f32_e32 v25, 1.0, v25
	v_mul_f32_e32 v23, v23, v66
	v_min_f32_e32 v27, 0x5affcb9e, v27
	v_mul_f32_e32 v26, v26, v66
	v_cvt_pk_bf16_f32 v23, v26, v23
	v_mul_f32_e32 v25, v40, v25
	v_add_f32_e32 v16, v24, v16
	v_mul_f32_e32 v26, v40, v27
	v_cvt_pk_bf16_f32 v25, v26, v25
	ds_write_b16 v182, v23 offset:864
	ds_write_b16_d16_hi v182, v23 offset:10080
	ds_write_b16 v182, v25 offset:19296
	v_exp_f32_e32 v23, v16
	v_min_f32_e64 v16, -v16, s33
	v_exp_f32_e32 v16, v16
	v_lshlrev_b32_e32 v44, 16, v44
	v_mul_f32_e32 v21, v21, v23
	v_min_f32_e32 v21, 0x5affcb9e, v21
	v_mul_f32_e32 v22, v22, v16
	v_mul_f32_e32 v16, v17, v16
	v_sub_f32_e32 v67, 1.0, v162
	v_min_f32_e32 v22, 0x5affcb9e, v22
	v_min_f32_e32 v16, 1.0, v16
	v_mul_f32_e32 v17, v23, v44
	v_mul_f32_e32 v21, v21, v44
	v_lshrrev_b32_e32 v24, 16, v25
	v_cvt_pk_bf16_f32 v17, v17, v21
	v_mul_f32_e32 v21, v67, v22
	v_mul_f32_e32 v16, v67, v16
	v_cvt_pk_bf16_f32 v16, v21, v16
	v_perm_b32 v63, v63, v62, s7
	v_and_or_b32 v21, v16, s13, v24
	v_perm_b32 v62, v61, v60, s7
	v_perm_b32 v61, v59, v58, s7
	v_perm_b32 v60, v57, v55, s7
	v_perm_b32 v49, v52, v50, s7
	v_perm_b32 v48, v47, v45, s7
	v_perm_b32 v47, v43, v41, s7
	v_perm_b32 v46, v37, v35, s7
	ds_write_b16 v182, v17 offset:1008
	ds_write_b16_d16_hi v182, v17 offset:10224
	ds_write_b16 v182, v16 offset:19440
	ds_write_b128 v154, v[18:21] offset:27648
	ds_write_b128 v155, v[46:49] offset:36864
	ds_write_b128 v183, v[60:63] offset:36880
	s_waitcnt lgkmcnt(0)
	s_barrier
	v_add_u32_e32 v16, v127, v101
	v_add_u32_e32 v17, v127, v119
	ds_read_b128 v[56:59], v16
	ds_read_b128 v[60:63], v17
	v_add_u32_e32 v16, v127, v120
	v_add_u32_e32 v17, v127, v121
	ds_read_b128 v[64:67], v16
	ds_read_b128 v[68:71], v17
	ds_read_b128 v[72:75], v156 offset:18432
	ds_read_b128 v[44:47], v156 offset:18496
	ds_read_b128 v[24:27], v173 offset:9216
	ds_read_b128 v[52:55], v173 offset:9280
	ds_read_b128 v[80:83], v173 offset:11520
	ds_read_b128 v[48:51], v173 offset:11584
	ds_read_b128 v[76:79], v156
	ds_read_b128 v[16:19], v156 offset:64
	ds_read_b128 v[40:43], v139
	ds_read_b128 v[36:39], v140
	ds_read_b128 v[32:35], v141
	ds_read_b128 v[20:23], v142
	v_mov_b32_e32 v145, v144
	v_mov_b32_e32 v146, v144
	v_mov_b32_e32 v147, v144
	v_mov_b64_e32 v[28:29], v[144:145]
	v_mov_b64_e32 v[30:31], v[146:147]
	s_and_saveexec_b64 s[26:27], s[44:45]
	s_cbranch_execz .LBB0_236
	s_waitcnt lgkmcnt(9)
	v_mfma_f32_16x16x32_bf16 v[28:31], v[72:75], v[24:27], 0
